# priority for the slot != 0 wave of each SIMD during the page streaming (slot-0 raise kept in attention/queue and LayerNorm phases)
# speedup vs baseline: 1.0157x; 1.0025x over previous
.Lma_s1:
	s_getreg_b32 s100, hwreg(HW_REG_HW_ID, 0, 4)
	s_cmp_lg_u32 s100, 0
	s_cbranch_scc0 .Lprio_done_s1
	s_setprio 1

.LBB0_332:
	s_setprio 0
	s_cmp_eq_u32 s101, 3
	s_cbranch_scc1 .Lma_fin
	s_mov_b32 s6, s23
	s_getreg_b32 s0, hwreg(HW_REG_HW_ID, 0, 6)
	s_and_b32 s0, s0, 63
	s_lshl_b32 s0, s0, 2
	s_add_i32 s0, s0, 0
	s_add_i32 s0, s0, 0x20400
	v_mov_b32_e32 v0, s0
	ds_read_b32 v2, v0
	v_readlane_b32 s0, v254, 2
	s_mov_b32 s2, s0
	v_mbcnt_lo_u32_b32 v0, -1, 0
	v_mbcnt_hi_u32_b32 v0, -1, v0
	s_waitcnt lgkmcnt(0)
	v_readfirstlane_b32 s0, v2
	s_and_b32 s1, s2, 7
	s_mov_b32 s4, s92
	v_lshl_add_u32 v2, s0, 6, v0
	s_cmp_eq_u32 s1, 0
	v_readfirstlane_b32 s0, v2
	s_cbranch_scc0 .LBB0_334
	s_ashr_i32 s3, s4, 31
	s_lshr_b32 s3, s3, 29
	s_add_i32 s3, s4, s3
	s_ashr_i32 s5, s3, 3
	s_and_b32 s3, s3, -8
	s_ashr_i32 s1, s2, 3
	s_sub_i32 s3, s4, s3
	s_mul_i32 s1, s3, s1
	s_add_i32 s4, s1, s5
